# adds gMLP unit load hoisting (all v-tile, gain, stat loads issued up front)
# baseline (speedup 1.0000x reference)
; #define LAS __attribute__((address_space(3)))
; DI unsigned pk2(float lo, float hi) { fv2 v = {lo, hi}; return __builtin_bit_cast(unsigned, __builtin_convertvector(v, bfv2)); }
; DI float bflo(unsigned w) { return __uint_as_float(w << 16); }
; DI float bfhi(unsigned w) { return __uint_as_float(w & 0xffff0000u); }
; DI void gm_unit(LAS unsigned char* lds, const bf16_t* Zrow0  , int nvalid, int gch, const bf16_t* Wsb, const float* bs, const float* gmg, const float* sv,
;                 bf16_t* OG  , int tid, int wid, int lane, bool loadW = true) {
;     LAS unsigned char* Wl = lds; LAS unsigned char* Vt = lds + 128 * 272;
;     if (loadW)
; #pragma unroll
;     for (int j = 0; j < 4; ++j) { const int p = tid + 512 * j, pr = p >> 4, c8 = p & 15; *(LAS u32x4*)(Wl + pr * 272 + c8 * 16) = *(const u32x4*)(Wsb + (size_t)gch * 16384 + pr * 128 + c8 * 8); }
; #pragma unroll
;     for (int j = 0; j < 4; ++j) {
;         const int p = tid + 512 * j, q = p & 127, cg = p >> 7;
;         u32x4 w = {0u, 0u, 0u, 0u}; float rs = 0.f;
;         if (q < nvalid) { w = *(const u32x4*)(Zrow0 + (size_t)q * NZ + ZV + gch * 128 + cg * 8); rs = rsqrtf(sv[q] * (1.0f / 1024.0f) + EPS); }
;         const f32x4 g0 = *(const f32x4*)(gmg + gch * 128 + cg * 8), g1 = *(const f32x4*)(gmg + gch * 128 + cg * 8 + 4);
;         float e[8] = {bflo(w.x) * g0[0], bfhi(w.x) * g0[1], bflo(w.y) * g0[2], bfhi(w.y) * g0[3], bflo(w.z) * g1[0], bfhi(w.z) * g1[1], bflo(w.w) * g1[2], bfhi(w.w) * g1[3]};
; #pragma unroll
;         for (int k = 0; k < 8; ++k) { const unsigned pw = pk2(e[k] * rs, 0.f); *(LAS unsigned short*)(Vt + (cg * 8 + k) * 272 + q * 2) = (unsigned short)(pw & 0xffffu); }
;     }
.LBB0_1373:
	s_and_b32 s24, s22, 7
	v_readlane_b32 s12, v252, 7
	v_readlane_b32 s13, v252, 8
	s_cmp_lg_u32 s22, s12
	v_readlane_b32 s14, v254, 20
	s_cselect_b64 s[12:13], -1, 0
	v_readlane_b32 s15, v254, 21
	s_and_b64 s[12:13], s[14:15], s[12:13]
	s_and_b64 vcc, exec, s[12:13]
	s_cbranch_vccnz .LBB0_1375
	s_lshl_b32 s90, s24, 15
	v_lshl_add_u64 v[6:7], v[18:19], 0, s[90:91]
	v_lshl_add_u64 v[164:165], v[20:21], 1, v[6:7]
	v_lshl_add_u64 v[166:167], v[22:23], 1, v[6:7]
	v_lshl_add_u64 v[168:169], v[24:25], 1, v[6:7]
	v_lshl_add_u64 v[170:171], v[26:27], 1, v[6:7]
	global_load_dwordx4 v[148:151], v[164:165], off
	global_load_dwordx4 v[152:155], v[166:167], off
	global_load_dwordx4 v[156:159], v[168:169], off
	global_load_dwordx4 v[160:163], v[170:171], off
	s_waitcnt vmcnt(3)
	ds_write_b128 v58, v[148:151]
	s_waitcnt vmcnt(2)
	ds_write_b128 v59, v[152:155]
	s_waitcnt vmcnt(1)
	ds_write_b128 v60, v[156:159]
	s_waitcnt vmcnt(0)
	ds_write_b128 v61, v[160:163]
.LBB0_1375:
	s_ashr_i32 s12, s22, 7
	s_ashr_i32 s13, s12, 31
	s_lshl_b32 s14, s22, 4
	s_lshl_b64 s[12:13], s[12:13], 11
	s_and_b32 s14, s14, 0x780
	s_or_b32 s12, s12, s14
	s_mul_i32 s14, s13, 0x3600
	s_mul_hi_u32 s15, s12, 0x3600
	s_add_i32 s15, s15, s14
	s_mul_i32 s14, s12, 0x3600
	s_add_u32 s14, s18, s14
	s_addc_u32 s15, s19, s15
	s_lshl_b32 s23, s24, 7
	s_lshl_b32 s16, s24, 9
	s_waitcnt lgkmcnt(0)
	s_add_u32 s16, s10, s16
	s_addc_u32 s17, s11, 0
	v_lshl_add_u64 v[2:3], s[14:15], 0, v[28:29]
	s_lshl_b32 s90, s24, 8
	v_lshl_add_u64 v[2:3], v[2:3], 0, s[90:91]
	v_lshl_add_u64 v[8:9], s[12:13], 2, v[30:31]
	v_lshl_add_u64 v[80:81], v[32:33], 1, v[2:3]
	v_lshl_add_u64 v[82:83], v[34:35], 1, v[2:3]
	v_lshl_add_u64 v[84:85], v[36:37], 1, v[2:3]
	v_lshl_add_u64 v[86:87], v[38:39], 1, v[2:3]
	v_lshl_add_u64 v[88:89], v[32:33], 2, s[16:17]
	v_lshl_add_u64 v[90:91], v[34:35], 2, s[16:17]
	v_lshl_add_u64 v[92:93], v[36:37], 2, s[16:17]
	v_lshl_add_u64 v[94:95], v[38:39], 2, s[16:17]
	global_load_dword v96, v[8:9], off
	global_load_dwordx4 v[100:103], v[80:81], off offset:2048
	global_load_dwordx4 v[116:119], v[88:89], off offset:16
	global_load_dwordx4 v[120:123], v[88:89], off
	global_load_dwordx4 v[104:107], v[82:83], off offset:2048
	global_load_dwordx4 v[124:127], v[90:91], off offset:16
	global_load_dwordx4 v[128:131], v[90:91], off
	global_load_dwordx4 v[108:111], v[84:85], off offset:2048
	global_load_dwordx4 v[132:135], v[92:93], off offset:16
	global_load_dwordx4 v[136:139], v[92:93], off
	global_load_dwordx4 v[112:115], v[86:87], off offset:2048
	global_load_dwordx4 v[140:143], v[94:95], off offset:16
	global_load_dwordx4 v[144:147], v[94:95], off
	v_mov_b32_e32 v43, v56
	v_mov_b32_e32 v45, v55
	v_readlane_b32 s16, v254, 11
	s_waitcnt vmcnt(12)
	v_fmamk_f32 v8, v96, 0x3a800000, v225
	v_cmp_gt_f32_e32 vcc, s65, v8
	v_mul_f32_e32 v9, 0x4b800000, v8
	s_nop 0
	v_cndmask_b32_e32 v8, v8, v9, vcc
	v_rsq_f32_e32 v8, v8
	s_nop 0
	v_mul_f32_e32 v9, 0x45800000, v8
	v_cndmask_b32_e32 v14, v8, v9, vcc
	s_waitcnt vmcnt(9)
	v_lshlrev_b32_e32 v4, 16, v100
	v_mul_f32_e32 v4, v120, v4
	v_mul_f32_e32 v4, v4, v14
	v_cvt_pk_bf16_f32 v4, v4, s0
	ds_write_b16 v62, v4 offset:34816
	v_and_b32_e32 v5, 0xffff0000, v100
	v_mul_f32_e32 v5, v121, v5
	v_mul_f32_e32 v5, v5, v14
	v_cvt_pk_bf16_f32 v5, v5, s0
	ds_write_b16 v62, v5 offset:35088
	v_lshlrev_b32_e32 v6, 16, v101
	v_mul_f32_e32 v6, v122, v6
	v_mul_f32_e32 v6, v6, v14
	v_cvt_pk_bf16_f32 v6, v6, s0
	ds_write_b16 v62, v6 offset:35360
	v_and_b32_e32 v7, 0xffff0000, v101
	v_mul_f32_e32 v7, v123, v7
	v_mul_f32_e32 v7, v7, v14
	v_cvt_pk_bf16_f32 v7, v7, s0
	ds_write_b16 v62, v7 offset:35632
	v_lshlrev_b32_e32 v4, 16, v102
	v_mul_f32_e32 v4, v116, v4
	v_mul_f32_e32 v4, v4, v14
	v_cvt_pk_bf16_f32 v4, v4, s0
	ds_write_b16 v62, v4 offset:35904
	v_and_b32_e32 v5, 0xffff0000, v102
	v_mul_f32_e32 v5, v117, v5
	v_mul_f32_e32 v5, v5, v14
	v_cvt_pk_bf16_f32 v5, v5, s0
	ds_write_b16 v62, v5 offset:36176
	v_lshlrev_b32_e32 v6, 16, v103
	v_mul_f32_e32 v6, v118, v6
	v_mul_f32_e32 v6, v6, v14
	v_cvt_pk_bf16_f32 v6, v6, s0
	ds_write_b16 v62, v6 offset:36448
	v_and_b32_e32 v7, 0xffff0000, v103
	v_mul_f32_e32 v7, v119, v7
	v_mul_f32_e32 v7, v7, v14
	v_cvt_pk_bf16_f32 v7, v7, s0
	ds_write_b16 v62, v7 offset:36720
	s_waitcnt vmcnt(6)
; #define LAS __attribute__((address_space(3)))
; DI unsigned pk2(float lo, float hi) { fv2 v = {lo, hi}; return __builtin_bit_cast(unsigned, __builtin_convertvector(v, bfv2)); }
; DI float bflo(unsigned w) { return __uint_as_float(w << 16); }
; DI float bfhi(unsigned w) { return __uint_as_float(w & 0xffff0000u); }
; DI void gm_unit(LAS unsigned char* lds, const bf16_t* Zrow0  , int nvalid, int gch, const bf16_t* Wsb, const float* bs, const float* gmg, const float* sv,
;                 bf16_t* OG  , int tid, int wid, int lane, bool loadW = true) {
;     ...
; #pragma unroll
;     for (int j = 0; j < 4; ++j) {
;         const int p = tid + 512 * j, q = p & 127, cg = p >> 7;
;         u32x4 w = {0u, 0u, 0u, 0u}; float rs = 0.f;
;         if (q < nvalid) { w = *(const u32x4*)(Zrow0 + (size_t)q * NZ + ZV + gch * 128 + cg * 8); rs = rsqrtf(sv[q] * (1.0f / 1024.0f) + EPS); }
;         const f32x4 g0 = *(const f32x4*)(gmg + gch * 128 + cg * 8), g1 = *(const f32x4*)(gmg + gch * 128 + cg * 8 + 4);
;         float e[8] = {bflo(w.x) * g0[0], bfhi(w.x) * g0[1], bflo(w.y) * g0[2], bfhi(w.y) * g0[3], bflo(w.z) * g1[0], bfhi(w.z) * g1[1], bflo(w.w) * g1[2], bfhi(w.w) * g1[3]};
; #pragma unroll
;         for (int k = 0; k < 8; ++k) { const unsigned pw = pk2(e[k] * rs, 0.f); *(LAS unsigned short*)(Vt + (cg * 8 + k) * 272 + q * 2) = (unsigned short)(pw & 0xffffu); }
;     }
;     __syncthreads();
	v_lshlrev_b32_e32 v4, 16, v104
	v_mul_f32_e32 v4, v128, v4
	v_mul_f32_e32 v4, v4, v14
	v_cvt_pk_bf16_f32 v4, v4, s0
	ds_write_b16 v63, v4 offset:34816
	v_and_b32_e32 v5, 0xffff0000, v104
	v_mul_f32_e32 v5, v129, v5
	v_mul_f32_e32 v5, v5, v14
	v_cvt_pk_bf16_f32 v5, v5, s0
	ds_write_b16 v63, v5 offset:35088
	v_lshlrev_b32_e32 v6, 16, v105
	v_mul_f32_e32 v6, v130, v6
	v_mul_f32_e32 v6, v6, v14
	v_cvt_pk_bf16_f32 v6, v6, s0
	ds_write_b16 v63, v6 offset:35360
	v_and_b32_e32 v7, 0xffff0000, v105
	v_mul_f32_e32 v7, v131, v7
	v_mul_f32_e32 v7, v7, v14
	v_cvt_pk_bf16_f32 v7, v7, s0
	ds_write_b16 v63, v7 offset:35632
	v_lshlrev_b32_e32 v4, 16, v106
	v_mul_f32_e32 v4, v124, v4
	v_mul_f32_e32 v4, v4, v14
	v_cvt_pk_bf16_f32 v4, v4, s0
	ds_write_b16 v63, v4 offset:35904
	v_and_b32_e32 v5, 0xffff0000, v106
	v_mul_f32_e32 v5, v125, v5
	v_mul_f32_e32 v5, v5, v14
	v_cvt_pk_bf16_f32 v5, v5, s0
	ds_write_b16 v63, v5 offset:36176
	v_lshlrev_b32_e32 v6, 16, v107
	v_mul_f32_e32 v6, v126, v6
	v_mul_f32_e32 v6, v6, v14
	v_cvt_pk_bf16_f32 v6, v6, s0
	ds_write_b16 v63, v6 offset:36448
	v_and_b32_e32 v7, 0xffff0000, v107
	v_mul_f32_e32 v7, v127, v7
	v_mul_f32_e32 v7, v7, v14
	v_cvt_pk_bf16_f32 v7, v7, s0
	ds_write_b16 v63, v7 offset:36720
	s_waitcnt vmcnt(3)
	v_lshlrev_b32_e32 v4, 16, v108
	v_mul_f32_e32 v4, v136, v4
	v_mul_f32_e32 v4, v4, v14
	v_cvt_pk_bf16_f32 v4, v4, s0
	ds_write_b16 v64, v4 offset:34816
	v_and_b32_e32 v5, 0xffff0000, v108
	v_mul_f32_e32 v5, v137, v5
	v_mul_f32_e32 v5, v5, v14
	v_cvt_pk_bf16_f32 v5, v5, s0
	ds_write_b16 v64, v5 offset:35088
	v_lshlrev_b32_e32 v6, 16, v109
	v_mul_f32_e32 v6, v138, v6
	v_mul_f32_e32 v6, v6, v14
	v_cvt_pk_bf16_f32 v6, v6, s0
	ds_write_b16 v64, v6 offset:35360
	v_and_b32_e32 v7, 0xffff0000, v109
	v_mul_f32_e32 v7, v139, v7
	v_mul_f32_e32 v7, v7, v14
	v_cvt_pk_bf16_f32 v7, v7, s0
	ds_write_b16 v64, v7 offset:35632
	v_lshlrev_b32_e32 v4, 16, v110
	v_mul_f32_e32 v4, v132, v4
	v_mul_f32_e32 v4, v4, v14
	v_cvt_pk_bf16_f32 v4, v4, s0
	ds_write_b16 v64, v4 offset:35904
	v_and_b32_e32 v5, 0xffff0000, v110
	v_mul_f32_e32 v5, v133, v5
	v_mul_f32_e32 v5, v5, v14
	v_cvt_pk_bf16_f32 v5, v5, s0
	ds_write_b16 v64, v5 offset:36176
	v_lshlrev_b32_e32 v6, 16, v111
	v_mul_f32_e32 v6, v134, v6
	v_mul_f32_e32 v6, v6, v14
	v_cvt_pk_bf16_f32 v6, v6, s0
	ds_write_b16 v64, v6 offset:36448
	v_and_b32_e32 v7, 0xffff0000, v111
	v_mul_f32_e32 v7, v135, v7
	v_mul_f32_e32 v7, v7, v14
	v_cvt_pk_bf16_f32 v7, v7, s0
	ds_write_b16 v64, v7 offset:36720
	s_waitcnt vmcnt(0)
	v_lshlrev_b32_e32 v4, 16, v112
	v_mul_f32_e32 v4, v144, v4
	v_mul_f32_e32 v4, v4, v14
	v_cvt_pk_bf16_f32 v4, v4, s0
	ds_write_b16 v65, v4 offset:34816
	v_and_b32_e32 v5, 0xffff0000, v112
	v_mul_f32_e32 v5, v145, v5
	v_mul_f32_e32 v5, v5, v14
	v_cvt_pk_bf16_f32 v5, v5, s0
	ds_write_b16 v65, v5 offset:35088
	v_lshlrev_b32_e32 v6, 16, v113
	v_mul_f32_e32 v6, v146, v6
	v_mul_f32_e32 v6, v6, v14
	v_cvt_pk_bf16_f32 v6, v6, s0
	ds_write_b16 v65, v6 offset:35360
	v_and_b32_e32 v7, 0xffff0000, v113
	v_mul_f32_e32 v7, v147, v7
	v_mul_f32_e32 v7, v7, v14
	v_cvt_pk_bf16_f32 v7, v7, s0
	ds_write_b16 v65, v7 offset:35632
	v_lshlrev_b32_e32 v4, 16, v114
	v_mul_f32_e32 v4, v140, v4
	v_mul_f32_e32 v4, v4, v14
	v_cvt_pk_bf16_f32 v4, v4, s0
	ds_write_b16 v65, v4 offset:35904
	v_and_b32_e32 v5, 0xffff0000, v114
	v_mul_f32_e32 v5, v141, v5
	v_mul_f32_e32 v5, v5, v14
	v_cvt_pk_bf16_f32 v5, v5, s0
	ds_write_b16 v65, v5 offset:36176
	v_lshlrev_b32_e32 v6, 16, v115
	v_mul_f32_e32 v6, v142, v6
	v_mul_f32_e32 v6, v6, v14
	v_cvt_pk_bf16_f32 v6, v6, s0
	ds_write_b16 v65, v6 offset:36448
	v_and_b32_e32 v7, 0xffff0000, v115
	v_mul_f32_e32 v7, v143, v7
	v_mul_f32_e32 v7, v7, v14
	v_cvt_pk_bf16_f32 v7, v7, s0
	ds_write_b16 v65, v7 offset:36720
	v_mov_b32_e32 v2, 0
	v_mov_b32_e32 v3, v2
	v_mov_b32_e32 v4, v2
	v_mov_b32_e32 v5, v2
	v_mov_b32_e32 v6, v2
	v_mov_b32_e32 v7, v2
	v_mov_b32_e32 v8, v2
	v_mov_b32_e32 v9, v2
	v_mov_b32_e32 v10, v2
	v_mov_b32_e32 v11, v2
	v_mov_b32_e32 v12, v2
	v_mov_b32_e32 v13, v2
	v_mov_b32_e32 v14, v2
	v_mov_b32_e32 v15, v2
	v_mov_b32_e32 v16, v2
	v_mov_b32_e32 v17, v2
	s_waitcnt lgkmcnt(0)
	s_barrier
